# NA tile loop: 32 rel-pos-bias LDS lookups per masked tile pipelined (12 in flight, counted lgkmcnt) instead of serialized
# baseline (speedup 1.0000x reference)
.LBB0_283:
	s_andn2_b64 vcc, exec, s[10:11]
	s_cbranch_vccnz .LBB0_280
	s_add_i32 s10, s24, 0xffffc000
	s_and_b32 s10, s10, 0x4000
	s_add_i32 s10, s10, 0
	v_add3_u32 v50, s10, v109, v108
	ds_read_b128 v[34:37], v50
	v_add3_u32 v94, s10, v110, v108
	ds_read_b128 v[130:133], v94
	ds_read_b128 v[50:53], v50 offset:4096
	s_andn2_b64 vcc, exec, s[72:73]
	s_waitcnt lgkmcnt(2)
	v_mfma_f32_32x32x16_bf16 v[34:49], v[34:37], v[78:81], 0
	s_waitcnt lgkmcnt(1)
	v_mfma_f32_32x32x16_bf16 v[34:49], v[130:133], v[74:77], v[34:49]
	ds_read_b128 v[130:133], v94 offset:4096
	v_add3_u32 v94, s10, v111, v108
	s_waitcnt lgkmcnt(1)
	v_mfma_f32_32x32x16_bf16 v[50:65], v[50:53], v[78:81], 0
	s_waitcnt lgkmcnt(0)
	v_mfma_f32_32x32x16_bf16 v[50:65], v[130:133], v[74:77], v[50:65]
	ds_read_b128 v[130:133], v94
	s_waitcnt lgkmcnt(0)
	v_mfma_f32_32x32x16_bf16 v[34:49], v[130:133], v[70:73], v[34:49]
	ds_read_b128 v[130:133], v94 offset:4096
	v_add3_u32 v94, s10, v112, v108
	s_waitcnt lgkmcnt(0)
	v_mfma_f32_32x32x16_bf16 v[50:65], v[130:133], v[70:73], v[50:65]
	ds_read_b128 v[130:133], v94
	s_waitcnt lgkmcnt(0)
	v_mfma_f32_32x32x16_bf16 v[34:49], v[130:133], v[66:69], v[34:49]
	ds_read_b128 v[130:133], v94 offset:4096
	s_waitcnt lgkmcnt(0)
	v_mfma_f32_32x32x16_bf16 v[50:65], v[130:133], v[66:69], v[50:65]
	s_cbranch_vccnz .LBB0_286
	v_cmp_ge_i32_e32 vcc, s3, v98
	v_cmp_lt_i32_e64 s[72:73], s3, v106
	s_and_b64 s[26:27], vcc, s[72:73]
	s_add_i32 s11, s3, 1
	v_cmp_ge_i32_e32 vcc, s11, v98
	v_cmp_lt_i32_e64 s[72:73], s11, v106
	s_and_b64 s[72:73], vcc, s[72:73]
	v_add_u32_e32 v94, s29, v125
	s_and_b64 vcc, s[26:27], s[68:69]
	v_add_u32_e32 v95, 0xffffff2f, v94
	v_cndmask_b32_e32 v95, 0, v95, vcc
	v_lshl_add_u32 v95, v95, 2, 0
	ds_read_b32 v148, v95 offset:32768
	s_and_b64 vcc, s[26:27], s[66:67]
	v_add_u32_e32 v95, 0xffffff30, v94
	v_cndmask_b32_e32 v95, 0, v95, vcc
	v_lshl_add_u32 v95, v95, 2, 0
	ds_read_b32 v149, v95 offset:32768
	s_and_b64 vcc, s[26:27], s[64:65]
	v_add_u32_e32 v95, 0xffffff31, v94
	v_cndmask_b32_e32 v95, 0, v95, vcc
	v_lshl_add_u32 v95, v95, 2, 0
	ds_read_b32 v150, v95 offset:32768
	s_and_b64 vcc, s[26:27], s[62:63]
	v_add_u32_e32 v95, 0xffffff32, v94
	v_cndmask_b32_e32 v95, 0, v95, vcc
	v_lshl_add_u32 v95, v95, 2, 0
	ds_read_b32 v151, v95 offset:32768
	s_and_b64 vcc, s[26:27], s[60:61]
	v_add_u32_e32 v95, 0xffffff37, v94
	v_cndmask_b32_e32 v95, 0, v95, vcc
	v_lshl_add_u32 v95, v95, 2, 0
	ds_read_b32 v152, v95 offset:32768
	s_and_b64 vcc, s[26:27], s[58:59]
	v_add_u32_e32 v95, 0xffffff38, v94
	v_cndmask_b32_e32 v95, 0, v95, vcc
	v_lshl_add_u32 v95, v95, 2, 0
	ds_read_b32 v153, v95 offset:32768
	s_and_b64 vcc, s[26:27], s[56:57]
	v_add_u32_e32 v95, 0xffffff39, v94
	v_cndmask_b32_e32 v95, 0, v95, vcc
	v_lshl_add_u32 v95, v95, 2, 0
	ds_read_b32 v154, v95 offset:32768
	s_and_b64 vcc, s[26:27], s[54:55]
	v_add_u32_e32 v95, 0xffffff3a, v94
	v_cndmask_b32_e32 v95, 0, v95, vcc
	v_lshl_add_u32 v95, v95, 2, 0
	ds_read_b32 v155, v95 offset:32768
	s_and_b64 vcc, s[26:27], s[52:53]
	v_add_u32_e32 v95, 0xffffff3f, v94
	v_cndmask_b32_e32 v95, 0, v95, vcc
	v_lshl_add_u32 v95, v95, 2, 0
	ds_read_b32 v156, v95 offset:32768
	s_and_b64 vcc, s[26:27], s[50:51]
	v_add_u32_e32 v95, 0xffffff40, v94
	v_cndmask_b32_e32 v95, 0, v95, vcc
	v_lshl_add_u32 v95, v95, 2, 0
	ds_read_b32 v157, v95 offset:32768
	s_and_b64 vcc, s[26:27], s[48:49]
	v_add_u32_e32 v95, 0xffffff41, v94
	v_cndmask_b32_e32 v95, 0, v95, vcc
	v_lshl_add_u32 v95, v95, 2, 0
	ds_read_b32 v158, v95 offset:32768
	s_and_b64 vcc, s[26:27], s[46:47]
	v_add_u32_e32 v95, 0xffffff42, v94
	v_cndmask_b32_e32 v95, 0, v95, vcc
	v_lshl_add_u32 v95, v95, 2, 0
	ds_read_b32 v159, v95 offset:32768
	s_waitcnt lgkmcnt(11)
	s_and_b64 vcc, s[26:27], s[68:69]
	v_add_f32_e32 v34, v34, v148
	v_cndmask_b32_e32 v34, v213, v34, vcc
	s_and_b64 vcc, s[26:27], s[44:45]
	v_add_u32_e32 v95, 0xffffff47, v94
	v_cndmask_b32_e32 v95, 0, v95, vcc
	v_lshl_add_u32 v95, v95, 2, 0
	ds_read_b32 v148, v95 offset:32768
	s_waitcnt lgkmcnt(11)
	s_and_b64 vcc, s[26:27], s[66:67]
	v_add_f32_e32 v35, v35, v149
	v_cndmask_b32_e32 v35, v213, v35, vcc
	s_and_b64 vcc, s[26:27], s[42:43]
	v_add_u32_e32 v95, 0xffffff48, v94
	v_cndmask_b32_e32 v95, 0, v95, vcc
	v_lshl_add_u32 v95, v95, 2, 0
	ds_read_b32 v149, v95 offset:32768
	s_waitcnt lgkmcnt(11)
	s_and_b64 vcc, s[26:27], s[64:65]
	v_add_f32_e32 v36, v36, v150
	v_cndmask_b32_e32 v36, v213, v36, vcc
	s_and_b64 vcc, s[26:27], s[40:41]
	v_add_u32_e32 v95, 0xffffff49, v94
	v_cndmask_b32_e32 v95, 0, v95, vcc
	v_lshl_add_u32 v95, v95, 2, 0
	ds_read_b32 v150, v95 offset:32768
	s_waitcnt lgkmcnt(11)
	s_and_b64 vcc, s[26:27], s[62:63]
	v_add_f32_e32 v37, v37, v151
	v_cndmask_b32_e32 v37, v213, v37, vcc
	s_and_b64 vcc, s[26:27], s[38:39]
	v_add_u32_e32 v95, 0xffffff4a, v94
	v_cndmask_b32_e32 v95, 0, v95, vcc
	v_lshl_add_u32 v95, v95, 2, 0
	ds_read_b32 v151, v95 offset:32768
	s_waitcnt lgkmcnt(11)
	s_and_b64 vcc, s[26:27], s[60:61]
	v_add_f32_e32 v38, v38, v152
	v_cndmask_b32_e32 v38, v213, v38, vcc
	s_and_b64 vcc, s[72:73], s[68:69]
	v_add_u32_e32 v95, 0xffffff4f, v94
	v_cndmask_b32_e32 v95, 0, v95, vcc
	v_lshl_add_u32 v95, v95, 2, 0
	ds_read_b32 v152, v95 offset:32768
	s_waitcnt lgkmcnt(11)
	s_and_b64 vcc, s[26:27], s[58:59]
	v_add_f32_e32 v39, v39, v153
	v_cndmask_b32_e32 v39, v213, v39, vcc
	s_and_b64 vcc, s[72:73], s[66:67]
	v_add_u32_e32 v95, 0xffffff50, v94
	v_cndmask_b32_e32 v95, 0, v95, vcc
	v_lshl_add_u32 v95, v95, 2, 0
	ds_read_b32 v153, v95 offset:32768
	s_waitcnt lgkmcnt(11)
	s_and_b64 vcc, s[26:27], s[56:57]
	v_add_f32_e32 v40, v40, v154
	v_cndmask_b32_e32 v40, v213, v40, vcc
	s_and_b64 vcc, s[72:73], s[64:65]
	v_add_u32_e32 v95, 0xffffff51, v94
	v_cndmask_b32_e32 v95, 0, v95, vcc
	v_lshl_add_u32 v95, v95, 2, 0
	ds_read_b32 v154, v95 offset:32768
	s_waitcnt lgkmcnt(11)
	s_and_b64 vcc, s[26:27], s[54:55]
	v_add_f32_e32 v41, v41, v155
	v_cndmask_b32_e32 v41, v213, v41, vcc
	s_and_b64 vcc, s[72:73], s[62:63]
	v_add_u32_e32 v95, 0xffffff52, v94
	v_cndmask_b32_e32 v95, 0, v95, vcc
	v_lshl_add_u32 v95, v95, 2, 0
	ds_read_b32 v155, v95 offset:32768
	s_waitcnt lgkmcnt(11)
	s_and_b64 vcc, s[26:27], s[52:53]
	v_add_f32_e32 v42, v42, v156
	v_cndmask_b32_e32 v42, v213, v42, vcc
	s_and_b64 vcc, s[72:73], s[60:61]
	v_add_u32_e32 v95, 0xffffff57, v94
	v_cndmask_b32_e32 v95, 0, v95, vcc
	v_lshl_add_u32 v95, v95, 2, 0
	ds_read_b32 v156, v95 offset:32768
	s_waitcnt lgkmcnt(11)
	s_and_b64 vcc, s[26:27], s[50:51]
	v_add_f32_e32 v43, v43, v157
	v_cndmask_b32_e32 v43, v213, v43, vcc
	s_and_b64 vcc, s[72:73], s[58:59]
	v_add_u32_e32 v95, 0xffffff58, v94
	v_cndmask_b32_e32 v95, 0, v95, vcc
	v_lshl_add_u32 v95, v95, 2, 0
	ds_read_b32 v157, v95 offset:32768
	s_waitcnt lgkmcnt(11)
	s_and_b64 vcc, s[26:27], s[48:49]
	v_add_f32_e32 v44, v44, v158
	v_cndmask_b32_e32 v44, v213, v44, vcc
	s_and_b64 vcc, s[72:73], s[56:57]
	v_add_u32_e32 v95, 0xffffff59, v94
	v_cndmask_b32_e32 v95, 0, v95, vcc
	v_lshl_add_u32 v95, v95, 2, 0
	ds_read_b32 v158, v95 offset:32768
	s_waitcnt lgkmcnt(11)
	s_and_b64 vcc, s[26:27], s[46:47]
	v_add_f32_e32 v45, v45, v159
	v_cndmask_b32_e32 v45, v213, v45, vcc
	s_and_b64 vcc, s[72:73], s[54:55]
	v_add_u32_e32 v95, 0xffffff5a, v94
	v_cndmask_b32_e32 v95, 0, v95, vcc
	v_lshl_add_u32 v95, v95, 2, 0
	ds_read_b32 v159, v95 offset:32768
	s_waitcnt lgkmcnt(11)
	s_and_b64 vcc, s[26:27], s[44:45]
	v_add_f32_e32 v46, v46, v148
	v_cndmask_b32_e32 v46, v213, v46, vcc
	s_and_b64 vcc, s[72:73], s[52:53]
	v_add_u32_e32 v95, 0xffffff5f, v94
	v_cndmask_b32_e32 v95, 0, v95, vcc
	v_lshl_add_u32 v95, v95, 2, 0
	ds_read_b32 v148, v95 offset:32768
	s_waitcnt lgkmcnt(11)
	s_and_b64 vcc, s[26:27], s[42:43]
	v_add_f32_e32 v47, v47, v149
	v_cndmask_b32_e32 v47, v213, v47, vcc
	s_and_b64 vcc, s[72:73], s[50:51]
	v_add_u32_e32 v95, 0xffffff60, v94
	v_cndmask_b32_e32 v95, 0, v95, vcc
	v_lshl_add_u32 v95, v95, 2, 0
	ds_read_b32 v149, v95 offset:32768
	s_waitcnt lgkmcnt(11)
	s_and_b64 vcc, s[26:27], s[40:41]
	v_add_f32_e32 v48, v48, v150
	v_cndmask_b32_e32 v48, v213, v48, vcc
	s_and_b64 vcc, s[72:73], s[48:49]
	v_add_u32_e32 v95, 0xffffff61, v94
	v_cndmask_b32_e32 v95, 0, v95, vcc
	v_lshl_add_u32 v95, v95, 2, 0
	ds_read_b32 v150, v95 offset:32768
	s_waitcnt lgkmcnt(11)
	s_and_b64 vcc, s[26:27], s[38:39]
	v_add_f32_e32 v49, v49, v151
	v_cndmask_b32_e32 v49, v213, v49, vcc
	s_and_b64 vcc, s[72:73], s[46:47]
	v_add_u32_e32 v95, 0xffffff62, v94
	v_cndmask_b32_e32 v95, 0, v95, vcc
	v_lshl_add_u32 v95, v95, 2, 0
	ds_read_b32 v151, v95 offset:32768
	s_waitcnt lgkmcnt(11)
	s_and_b64 vcc, s[72:73], s[68:69]
	v_add_f32_e32 v50, v50, v152
	v_cndmask_b32_e32 v50, v213, v50, vcc
	s_and_b64 vcc, s[72:73], s[44:45]
	v_add_u32_e32 v95, 0xffffff67, v94
	v_cndmask_b32_e32 v95, 0, v95, vcc
	v_lshl_add_u32 v95, v95, 2, 0
	ds_read_b32 v152, v95 offset:32768
	s_waitcnt lgkmcnt(11)
	s_and_b64 vcc, s[72:73], s[66:67]
	v_add_f32_e32 v51, v51, v153
	v_cndmask_b32_e32 v51, v213, v51, vcc
	s_and_b64 vcc, s[72:73], s[42:43]
	v_add_u32_e32 v95, 0xffffff68, v94
	v_cndmask_b32_e32 v95, 0, v95, vcc
	v_lshl_add_u32 v95, v95, 2, 0
	ds_read_b32 v153, v95 offset:32768
	s_waitcnt lgkmcnt(11)
	s_and_b64 vcc, s[72:73], s[64:65]
	v_add_f32_e32 v52, v52, v154
	v_cndmask_b32_e32 v52, v213, v52, vcc
	s_and_b64 vcc, s[72:73], s[40:41]
	v_add_u32_e32 v95, 0xffffff69, v94
	v_cndmask_b32_e32 v95, 0, v95, vcc
	v_lshl_add_u32 v95, v95, 2, 0
	ds_read_b32 v154, v95 offset:32768
	s_waitcnt lgkmcnt(11)
	s_and_b64 vcc, s[72:73], s[62:63]
	v_add_f32_e32 v53, v53, v155
	v_cndmask_b32_e32 v53, v213, v53, vcc
	s_and_b64 vcc, s[72:73], s[38:39]
	v_add_u32_e32 v95, 0xffffff6a, v94
	v_cndmask_b32_e32 v95, 0, v95, vcc
	v_lshl_add_u32 v95, v95, 2, 0
	ds_read_b32 v155, v95 offset:32768
	s_waitcnt lgkmcnt(11)
	s_and_b64 vcc, s[72:73], s[60:61]
	v_add_f32_e32 v54, v54, v156
	v_cndmask_b32_e32 v54, v213, v54, vcc
	s_waitcnt lgkmcnt(10)
	s_and_b64 vcc, s[72:73], s[58:59]
	v_add_f32_e32 v55, v55, v157
	v_cndmask_b32_e32 v55, v213, v55, vcc
	s_waitcnt lgkmcnt(9)
	s_and_b64 vcc, s[72:73], s[56:57]
	v_add_f32_e32 v56, v56, v158
	v_cndmask_b32_e32 v56, v213, v56, vcc
	s_waitcnt lgkmcnt(8)
	s_and_b64 vcc, s[72:73], s[54:55]
	v_add_f32_e32 v57, v57, v159
	v_cndmask_b32_e32 v57, v213, v57, vcc
	s_waitcnt lgkmcnt(7)
	s_and_b64 vcc, s[72:73], s[52:53]
	v_add_f32_e32 v58, v58, v148
	v_cndmask_b32_e32 v58, v213, v58, vcc
	s_waitcnt lgkmcnt(6)
	s_and_b64 vcc, s[72:73], s[50:51]
	v_add_f32_e32 v59, v59, v149
	v_cndmask_b32_e32 v59, v213, v59, vcc
	s_waitcnt lgkmcnt(5)
	s_and_b64 vcc, s[72:73], s[48:49]
	v_add_f32_e32 v60, v60, v150
	v_cndmask_b32_e32 v60, v213, v60, vcc
	s_waitcnt lgkmcnt(4)
	s_and_b64 vcc, s[72:73], s[46:47]
	v_add_f32_e32 v61, v61, v151
	v_cndmask_b32_e32 v61, v213, v61, vcc
	s_waitcnt lgkmcnt(3)
	s_and_b64 vcc, s[72:73], s[44:45]
	v_add_f32_e32 v62, v62, v152
	v_cndmask_b32_e32 v62, v213, v62, vcc
	s_waitcnt lgkmcnt(2)
	s_and_b64 vcc, s[72:73], s[42:43]
	v_add_f32_e32 v63, v63, v153
	v_cndmask_b32_e32 v63, v213, v63, vcc
	s_waitcnt lgkmcnt(1)
	s_and_b64 vcc, s[72:73], s[40:41]
	v_add_f32_e32 v64, v64, v154
	v_cndmask_b32_e32 v64, v213, v64, vcc
	s_waitcnt lgkmcnt(0)
	s_and_b64 vcc, s[72:73], s[38:39]
	v_add_f32_e32 v65, v65, v155
	v_cndmask_b32_e32 v65, v213, v65, vcc
